# RG-LRU: B fragments of the next gate cluster read one at a time through the store section (spread), cluster = single wait + 18 back-to-back MFMAs
# speedup vs baseline: 1.0054x; 1.0054x over previous
.LBB0_270:
	v_cndmask_b32_e64 v0, 1.0, v35, s[4:5]
	v_cndmask_b32_e64 v35, 0, v37, s[4:5]
	v_cndmask_b32_e64 v37, v38, v41, s[4:5]
	v_cndmask_b32_e64 v36, v36, v40, s[4:5]
	ds_read_b128 v[178:181], v145 offset:24576
	v_cndmask_b32_e64 v40, v46, v88, s[4:5]
	v_cndmask_b32_e64 v41, v43, v47, s[4:5]
	s_ashr_i32 s13, s12, 31
	v_lshlrev_b32_e32 v88, 2, v93
	v_fmac_f32_e32 v25, v32, v41
	v_mul_f32_e32 v32, v32, v40
	v_fmac_f32_e32 v9, v34, v36
	v_mul_f32_e32 v34, v34, v37
	ds_read_b128 v[182:185], v145 offset:57344
	v_fmac_f32_e32 v10, v31, v36
	v_mul_f32_e32 v31, v31, v37
	v_fmac_f32_e32 v5, v28, v36
	v_mul_f32_e32 v28, v28, v37
	v_fmac_f32_e32 v11, v18, v36
	v_mul_f32_e32 v18, v18, v37
	v_fmac_f32_e32 v6, v12, v35
	v_mul_f32_e32 v36, v0, v12
	ds_read_b128 v[186:189], v147 offset:24576
	v_fmac_f32_e32 v4, v13, v35
	v_mul_f32_e32 v37, v0, v13
	v_lshl_add_u64 v[12:13], s[24:25], 0, v[88:89]
	s_lshl_b64 s[6:7], s[12:13], 12
	v_lshl_add_u64 v[94:95], v[12:13], 0, s[6:7]
	v_mul_f32_e32 v13, v32, v8
	v_fmac_f32_e32 v23, v29, v41
	v_mul_f32_e32 v29, v29, v40
	ds_read_b128 v[190:193], v147 offset:57344
	v_fmac_f32_e32 v21, v26, v41
	v_mul_f32_e32 v26, v26, v40
	v_fmac_f32_e32 v3, v16, v41
	v_mul_f32_e32 v40, v16, v40
	v_lshlrev_b32_e32 v12, 14, v92
	v_fmac_f32_e32 v25, v32, v1
	v_cvt_pk_bf16_f32 v16, v25, v13
	v_mov_b32_e32 v13, v89
	v_cndmask_b32_e64 v38, v42, v45, s[4:5]
	ds_read_b128 v[194:197], v142 offset:24576
	v_cndmask_b32_e64 v39, v39, v44, s[4:5]
	v_lshl_add_u64 v[96:97], v[94:95], 0, v[12:13]
	v_mul_f32_e32 v13, v29, v8
	v_or_b32_e32 v88, 0x1000, v12
	v_fmac_f32_e32 v22, v33, v39
	v_mul_f32_e32 v33, v33, v38
	v_fmac_f32_e32 v20, v30, v39
	v_mul_f32_e32 v30, v30, v38
	ds_read_b128 v[198:201], v142 offset:57344
	v_fmac_f32_e32 v19, v27, v39
	v_mul_f32_e32 v27, v27, v38
	v_fmac_f32_e32 v7, v17, v39
	v_mul_f32_e32 v38, v17, v38
	v_lshl_or_b32 v175, v138, 2, v133
	global_load_dword v172, v175, s[42:43]
	global_load_dword v173, v175, s[36:37]
	global_load_dword v174, v175, s[40:41]
	ds_read_b128 v[202:205], v146 offset:24576
	global_store_dword v[96:97], v16, off nt
	v_fmac_f32_e32 v23, v29, v1
	v_cvt_pk_bf16_f32 v13, v23, v13
	v_lshl_add_u64 v[16:17], v[94:95], 0, v[88:89]
	global_store_dword v[16:17], v13, off nt
	v_mul_f32_e32 v13, v26, v8
	v_or_b32_e32 v98, 0x2000, v12
	v_mov_b32_e32 v99, v89
	v_fmac_f32_e32 v21, v26, v1
	v_cvt_pk_bf16_f32 v13, v21, v13
	ds_read_b128 v[206:209], v146 offset:57344
	v_lshl_add_u64 v[16:17], v[94:95], 0, v[98:99]
	v_fmac_f32_e32 v3, v40, v1
	v_or_b32_e32 v100, 0x3000, v12
	v_mov_b32_e32 v101, v89
	global_store_dword v[16:17], v13, off nt
	v_mul_f32_e32 v13, v40, v8
	v_cvt_pk_bf16_f32 v3, v3, v13
	v_lshl_add_u64 v[16:17], v[94:95], 0, v[100:101]
	global_store_dword v[16:17], v3, off nt
	ds_read_b128 v[210:213], v141 offset:24576
	v_mul_f32_e32 v3, v33, v8
	v_or_b32_e32 v102, 0x8000, v12
	v_mov_b32_e32 v103, v89
	v_fmac_f32_e32 v22, v33, v1
	v_cvt_pk_bf16_f32 v3, v22, v3
	v_lshl_add_u64 v[16:17], v[94:95], 0, v[102:103]
	global_store_dword v[16:17], v3, off nt
	v_mul_f32_e32 v3, v30, v8
	v_or_b32_e32 v104, 0x9000, v12
	ds_read_b128 v[214:217], v141 offset:57344
	v_mov_b32_e32 v105, v89
	v_fmac_f32_e32 v20, v30, v1
	v_cvt_pk_bf16_f32 v3, v20, v3
	v_lshl_add_u64 v[16:17], v[94:95], 0, v[104:105]
	global_store_dword v[16:17], v3, off nt
	v_mul_f32_e32 v3, v27, v8
	v_or_b32_e32 v106, 0xa000, v12
	v_mov_b32_e32 v107, v89
	v_fmac_f32_e32 v19, v27, v1
	v_cvt_pk_bf16_f32 v3, v19, v3
	ds_read_b128 v[218:221], v144 offset:24576
	v_lshl_add_u64 v[16:17], v[94:95], 0, v[106:107]
	global_store_dword v[16:17], v3, off nt
	v_mul_f32_e32 v3, v38, v8
	v_or_b32_e32 v108, 0xb000, v12
	v_mov_b32_e32 v109, v89
	v_fmac_f32_e32 v7, v38, v1
	v_cvt_pk_bf16_f32 v3, v7, v3
	v_lshl_add_u64 v[16:17], v[94:95], 0, v[108:109]
	global_store_dword v[16:17], v3, off nt
	ds_read_b128 v[222:225], v144 offset:57344
	v_mul_f32_e32 v3, v34, v8
	v_or_b32_e32 v110, 0x10000, v12
	v_mov_b32_e32 v111, v89
	v_fmac_f32_e32 v9, v34, v1
	v_cvt_pk_bf16_f32 v3, v9, v3
	v_lshl_add_u64 v[16:17], v[94:95], 0, v[110:111]
	global_store_dword v[16:17], v3, off nt
	v_mul_f32_e32 v3, v31, v8
	v_or_b32_e32 v112, 0x11000, v12
	ds_read_b128 v[226:229], v139 offset:24576
	v_mov_b32_e32 v113, v89
	v_fmac_f32_e32 v10, v31, v1
	v_cvt_pk_bf16_f32 v3, v10, v3
	v_lshl_add_u64 v[16:17], v[94:95], 0, v[112:113]
	global_store_dword v[16:17], v3, off nt
	v_mul_f32_e32 v3, v28, v8
	v_or_b32_e32 v114, 0x12000, v12
	v_mov_b32_e32 v115, v89
	v_fmac_f32_e32 v5, v28, v1
	v_cvt_pk_bf16_f32 v3, v5, v3
	ds_read_b128 v[230:233], v139 offset:57344
	v_lshl_add_u64 v[16:17], v[94:95], 0, v[114:115]
	global_store_dword v[16:17], v3, off nt
	v_fmac_f32_e32 v11, v18, v1
	v_mul_f32_e32 v3, v18, v8
	v_or_b32_e32 v116, 0x13000, v12
	v_mov_b32_e32 v117, v89
	v_cvt_pk_bf16_f32 v3, v11, v3
	v_lshl_add_u64 v[10:11], v[94:95], 0, v[116:117]
	global_store_dword v[10:11], v3, off nt
	ds_read_b128 v[234:237], v143 offset:24576
	v_fmac_f32_e32 v6, v36, v1
	v_mul_f32_e32 v3, v36, v8
	v_or_b32_e32 v118, 0x18000, v12
	v_mov_b32_e32 v119, v89
	v_cvt_pk_bf16_f32 v3, v6, v3
	v_lshl_add_u64 v[6:7], v[94:95], 0, v[118:119]
	global_store_dword v[6:7], v3, off nt
	v_fmac_f32_e32 v4, v37, v1
	v_mul_f32_e32 v3, v37, v8
	ds_read_b128 v[238:241], v143 offset:57344
	v_or_b32_e32 v120, 0x19000, v12
	v_mov_b32_e32 v121, v89
	v_fmac_f32_e32 v2, v14, v35
	v_mul_f32_e32 v14, v0, v14
	v_cvt_pk_bf16_f32 v3, v4, v3
	v_lshl_add_u64 v[4:5], v[94:95], 0, v[120:121]
	v_fmac_f32_e32 v15, v24, v35
	v_mul_f32_e32 v0, v0, v24
	s_lshl_b32 s8, s65, 11
	global_store_dword v[4:5], v3, off nt
	v_fmac_f32_e32 v2, v14, v1
	v_mul_f32_e32 v3, v14, v8
	v_or_b32_e32 v122, 0x1a000, v12
	v_mov_b32_e32 v123, v89
	s_or_b32 s8, s8, s76
	v_cvt_pk_bf16_f32 v4, v2, v3
	v_lshl_add_u64 v[2:3], v[94:95], 0, v[122:123]
	v_fmac_f32_e32 v15, v0, v1
	v_mul_f32_e32 v0, v0, v8
	v_or_b32_e32 v124, 0x1b000, v12
	v_mov_b32_e32 v125, v89
	v_cmp_gt_i32_e64 s[6:7], 32, v90
	v_add_u32_e32 v92, s8, v90
	global_store_dword v[2:3], v4, off nt
	v_cvt_pk_bf16_f32 v2, v15, v0
	v_lshl_add_u64 v[0:1], v[94:95], 0, v[124:125]
	v_lshl_add_u32 v90, v90, 3, 16
	global_store_dword v[0:1], v2, off nt
	s_and_saveexec_b64 s[8:9], s[6:7]
	s_cbranch_execz .LBB0_272
	ds_read2_b64 v[0:3], v90 offset0:192 offset1:224
	ds_read2_b64 v[4:7], v90 offset0:128 offset1:160
	ds_read2_b64 v[8:11], v90 offset0:64 offset1:96
	ds_read2_b64 v[12:15], v90 offset1:32
	v_ashrrev_i32_e32 v93, 31, v92
	s_waitcnt lgkmcnt(3)
	v_fma_f32 v16, 0, v2, v3
	v_pk_mul_f32 v[2:3], v[2:3], v[0:1]
	v_fma_f32 v0, v0, v16, v1
	s_waitcnt lgkmcnt(2)
	v_fma_f32 v0, v6, v0, v7
	v_fma_f32 v0, v4, v0, v5
	s_waitcnt lgkmcnt(1)
	v_fma_f32 v1, v10, v0, v11
	v_mov_b32_e32 v0, v2
	v_mov_b32_e32 v16, v6
	v_mov_b32_e32 v17, v8
	v_pk_mul_f32 v[2:3], v[2:3], v[6:7]
	v_pk_fma_f32 v[0:1], v[0:1], v[16:17], v[8:9]
	v_pk_mul_f32 v[2:3], v[2:3], v[4:5]
	s_waitcnt lgkmcnt(0)
	v_mov_b32_e32 v11, v14
	v_mov_b32_e32 v3, v1
	v_pk_mul_f32 v[0:1], v[2:3], v[10:11]
	v_pk_fma_f32 v[2:3], v[2:3], v[10:11], v[14:15]
	v_pk_mul_f32 v[0:1], v[0:1], v[8:9]
	v_mov_b32_e32 v4, v14
	v_mov_b32_e32 v2, v0
	v_mov_b32_e32 v5, v12
	v_pk_mul_f32 v[0:1], v[0:1], v[14:15]
	v_pk_fma_f32 v[2:3], v[2:3], v[4:5], v[12:13]
	v_pk_mul_f32 v[0:1], v[0:1], v[12:13]
	s_nop 0
	v_mov_b32_e32 v1, v3
	v_lshl_add_u64 v[2:3], v[92:93], 3, s[30:31]
	global_store_dwordx2 v[2:3], v[0:1], off

.LBB0_278:
	v_cndmask_b32_e64 v0, 1.0, v35, s[4:5]
	v_cndmask_b32_e64 v35, 0, v37, s[4:5]
	v_cndmask_b32_e64 v37, v38, v41, s[4:5]
	v_cndmask_b32_e64 v36, v36, v40, s[4:5]
	ds_read_b128 v[178:181], v145 offset:32768
	v_cndmask_b32_e64 v40, v46, v93, s[4:5]
	v_cndmask_b32_e64 v41, v43, v47, s[4:5]
	v_fmac_f32_e32 v25, v32, v41
	v_mul_f32_e32 v32, v32, v40
	v_fmac_f32_e32 v23, v29, v41
	v_mul_f32_e32 v29, v29, v40
	ds_read_b128 v[182:185], v147 offset:32768
	v_fmac_f32_e32 v20, v26, v41
	v_mul_f32_e32 v26, v26, v40
	v_fmac_f32_e32 v3, v16, v41
	v_mul_f32_e32 v40, v16, v40
	v_mul_f32_e32 v16, v32, v8
	v_fmac_f32_e32 v25, v32, v1
	v_cvt_pk_bf16_f32 v16, v25, v16
	v_add_u32_e32 v242, 0x8000, v145
	ds_read_b128 v[186:189], v242 offset:32768
	v_cndmask_b32_e64 v38, v42, v45, s[4:5]
	v_cndmask_b32_e64 v39, v39, v44, s[4:5]
	v_fmac_f32_e32 v10, v34, v36
	v_mul_f32_e32 v34, v34, v37
	v_fmac_f32_e32 v6, v31, v36
	v_mul_f32_e32 v31, v31, v37
	v_add_u32_e32 v242, 0x8000, v147
	ds_read_b128 v[190:193], v242 offset:32768
	v_fmac_f32_e32 v4, v28, v36
	v_mul_f32_e32 v28, v28, v37
	v_fmac_f32_e32 v11, v18, v36
	v_mul_f32_e32 v18, v18, v37
	v_fmac_f32_e32 v9, v12, v35
	v_mul_f32_e32 v36, v0, v12
	ds_read_b128 v[194:197], v142 offset:32768
	v_fmac_f32_e32 v5, v13, v35
	v_mul_f32_e32 v37, v0, v13
	v_lshl_add_u64 v[12:13], v[94:95], 0, s[48:49]
	v_lshl_or_b32 v175, v138, 2, v134
	global_load_dword v172, v175, s[42:43]
	global_load_dword v173, v175, s[36:37]
	ds_read_b128 v[198:201], v146 offset:32768
	global_load_dword v174, v175, s[40:41]
	global_store_dword v[96:97], v16, off offset:128 nt
	v_mul_f32_e32 v16, v29, v8
	v_fmac_f32_e32 v24, v33, v39
	v_mul_f32_e32 v33, v33, v38
	v_fmac_f32_e32 v21, v30, v39
	v_add_u32_e32 v242, 0x8000, v146
	ds_read_b128 v[202:205], v242 offset:32768
	v_mul_f32_e32 v30, v30, v38
	v_fmac_f32_e32 v19, v27, v39
	v_mul_f32_e32 v27, v27, v38
	v_fmac_f32_e32 v7, v17, v39
	v_mul_f32_e32 v38, v17, v38
	v_fmac_f32_e32 v2, v14, v35
	v_add_u32_e32 v242, 0x8000, v142
	ds_read_b128 v[206:209], v242 offset:32768
	v_mul_f32_e32 v14, v0, v14
	v_fmac_f32_e32 v15, v22, v35
	v_mul_f32_e32 v0, v0, v22
	v_fmac_f32_e32 v23, v29, v1
	v_cvt_pk_bf16_f32 v22, v23, v16
	v_lshl_add_u64 v[16:17], v[12:13], 0, v[88:89]
	global_store_dword v[16:17], v22, off nt
	ds_read_b128 v[210:213], v141 offset:32768
	v_fmac_f32_e32 v20, v26, v1
	v_mul_f32_e32 v16, v26, v8
	v_cvt_pk_bf16_f32 v20, v20, v16
	v_lshl_add_u64 v[16:17], v[12:13], 0, v[98:99]
	global_store_dword v[16:17], v20, off nt
	v_fmac_f32_e32 v3, v40, v1
	v_mul_f32_e32 v16, v40, v8
	v_cvt_pk_bf16_f32 v3, v3, v16
	ds_read_b128 v[214:217], v144 offset:32768
	v_lshl_add_u64 v[16:17], v[12:13], 0, v[100:101]
	global_store_dword v[16:17], v3, off nt
	v_mul_f32_e32 v3, v33, v8
	v_fmac_f32_e32 v24, v33, v1
	v_cvt_pk_bf16_f32 v3, v24, v3
	v_lshl_add_u64 v[16:17], v[12:13], 0, v[102:103]
	global_store_dword v[16:17], v3, off nt
	v_add_u32_e32 v242, 0x8000, v144
	ds_read_b128 v[218:221], v242 offset:32768
	v_mul_f32_e32 v3, v30, v8
	v_fmac_f32_e32 v21, v30, v1
	v_cvt_pk_bf16_f32 v3, v21, v3
	v_lshl_add_u64 v[16:17], v[12:13], 0, v[104:105]
	global_store_dword v[16:17], v3, off nt
	v_mul_f32_e32 v3, v27, v8
	v_fmac_f32_e32 v19, v27, v1
	v_cvt_pk_bf16_f32 v3, v19, v3
	v_add_u32_e32 v242, 0x8000, v141
	ds_read_b128 v[222:225], v242 offset:32768
	v_lshl_add_u64 v[16:17], v[12:13], 0, v[106:107]
	global_store_dword v[16:17], v3, off nt
	v_mul_f32_e32 v3, v38, v8
	v_fmac_f32_e32 v7, v38, v1
	v_cvt_pk_bf16_f32 v3, v7, v3
	v_lshl_add_u64 v[16:17], v[12:13], 0, v[108:109]
	global_store_dword v[16:17], v3, off nt
	ds_read_b128 v[226:229], v139 offset:32768
	v_mul_f32_e32 v3, v34, v8
	v_fmac_f32_e32 v10, v34, v1
	v_cvt_pk_bf16_f32 v3, v10, v3
	v_lshl_add_u64 v[16:17], v[12:13], 0, v[110:111]
	global_store_dword v[16:17], v3, off nt
	v_fmac_f32_e32 v6, v31, v1
	v_mul_f32_e32 v3, v31, v8
	v_cvt_pk_bf16_f32 v3, v6, v3
	ds_read_b128 v[230:233], v143 offset:32768
	v_lshl_add_u64 v[6:7], v[12:13], 0, v[112:113]
	global_store_dword v[6:7], v3, off nt
	v_mul_f32_e32 v3, v28, v8
	v_fmac_f32_e32 v4, v28, v1
	v_cvt_pk_bf16_f32 v3, v4, v3
	v_lshl_add_u64 v[6:7], v[12:13], 0, v[114:115]
	global_store_dword v[6:7], v3, off nt
	v_add_u32_e32 v242, 0x8000, v143
	ds_read_b128 v[234:237], v242 offset:32768
	v_mul_f32_e32 v3, v18, v8
	v_fmac_f32_e32 v11, v18, v1
	v_cvt_pk_bf16_f32 v3, v11, v3
	v_lshl_add_u64 v[6:7], v[12:13], 0, v[116:117]
	global_store_dword v[6:7], v3, off nt
	v_mul_f32_e32 v3, v36, v8
	v_fmac_f32_e32 v9, v36, v1
	v_cvt_pk_bf16_f32 v3, v9, v3
	v_add_u32_e32 v242, 0x8000, v139
	ds_read_b128 v[238:241], v242 offset:32768
	v_lshl_add_u64 v[6:7], v[12:13], 0, v[118:119]
	global_store_dword v[6:7], v3, off nt
	v_fmac_f32_e32 v5, v37, v1
	v_mul_f32_e32 v3, v37, v8
	v_cvt_pk_bf16_f32 v3, v5, v3
	v_lshl_add_u64 v[4:5], v[12:13], 0, v[120:121]
	global_store_dword v[4:5], v3, off nt
	v_fmac_f32_e32 v2, v14, v1
	v_mul_f32_e32 v3, v14, v8
	v_cvt_pk_bf16_f32 v4, v2, v3
	v_lshl_add_u64 v[2:3], v[12:13], 0, v[122:123]
	v_fmac_f32_e32 v15, v0, v1
	v_mul_f32_e32 v0, v0, v8
	global_store_dword v[2:3], v4, off nt
	v_cvt_pk_bf16_f32 v2, v15, v0
	v_lshl_add_u64 v[0:1], v[12:13], 0, v[124:125]
	global_store_dword v[0:1], v2, off nt
	s_and_saveexec_b64 s[12:13], s[6:7]
	s_cbranch_execz .LBB0_280
	v_add_u32_e32 v12, 0x800, v90
	ds_read2_b64 v[0:3], v12 offset0:192 offset1:224
	ds_read2_b64 v[4:7], v12 offset0:128 offset1:160
	ds_read2_b64 v[8:11], v12 offset0:64 offset1:96
	ds_read2_b64 v[12:15], v12 offset1:32
	s_waitcnt lgkmcnt(3)
	v_fma_f32 v16, 0, v2, v3
	v_pk_mul_f32 v[2:3], v[2:3], v[0:1]
	v_fma_f32 v0, v0, v16, v1
	s_waitcnt lgkmcnt(2)
	v_fma_f32 v0, v6, v0, v7
	v_fma_f32 v0, v4, v0, v5
	s_waitcnt lgkmcnt(1)
	v_fma_f32 v1, v10, v0, v11
	v_mov_b32_e32 v0, v2
	v_mov_b32_e32 v16, v6
	v_mov_b32_e32 v17, v8
	v_pk_mul_f32 v[2:3], v[2:3], v[6:7]
	v_pk_fma_f32 v[0:1], v[0:1], v[16:17], v[8:9]
	v_pk_mul_f32 v[2:3], v[2:3], v[4:5]
	s_waitcnt lgkmcnt(0)
	v_mov_b32_e32 v11, v14
	v_mov_b32_e32 v3, v1
	v_pk_mul_f32 v[0:1], v[2:3], v[10:11]
	v_pk_fma_f32 v[2:3], v[2:3], v[10:11], v[14:15]
	v_pk_mul_f32 v[0:1], v[0:1], v[8:9]
	v_mov_b32_e32 v4, v14
	v_mov_b32_e32 v2, v0
	v_mov_b32_e32 v5, v12
	v_pk_mul_f32 v[0:1], v[0:1], v[14:15]
	v_pk_fma_f32 v[2:3], v[2:3], v[4:5], v[12:13]
	v_pk_mul_f32 v[0:1], v[0:1], v[12:13]
	v_add_u32_e32 v2, 32, v92
	v_mov_b32_e32 v1, v3
	v_ashrrev_i32_e32 v3, 31, v2
	v_lshl_add_u64 v[2:3], v[2:3], 3, s[30:31]
	global_store_dwordx2 v[2:3], v[0:1], off

.LBB0_286:
	v_cndmask_b32_e64 v0, 1.0, v35, s[4:5]
	v_cndmask_b32_e64 v35, 0, v37, s[4:5]
	v_cndmask_b32_e64 v37, v38, v41, s[4:5]
	v_cndmask_b32_e64 v36, v36, v40, s[4:5]
	ds_read_b128 v[178:181], v145 offset:40960
	v_cndmask_b32_e64 v40, v46, v93, s[4:5]
	v_cndmask_b32_e64 v41, v43, v47, s[4:5]
	v_fmac_f32_e32 v25, v32, v41
	v_mul_f32_e32 v32, v32, v40
	v_fmac_f32_e32 v23, v29, v41
	v_mul_f32_e32 v29, v29, v40
	ds_read_b128 v[182:185], v147 offset:40960
	v_fmac_f32_e32 v20, v26, v41
	v_mul_f32_e32 v26, v26, v40
	v_fmac_f32_e32 v3, v16, v41
	v_mul_f32_e32 v40, v16, v40
	v_mul_f32_e32 v16, v32, v8
	v_fmac_f32_e32 v25, v32, v1
	v_cvt_pk_bf16_f32 v16, v25, v16
	v_add_u32_e32 v242, 0xa000, v145
	ds_read_b128 v[186:189], v242 offset:32768
	v_cndmask_b32_e64 v38, v42, v45, s[4:5]
	v_cndmask_b32_e64 v39, v39, v44, s[4:5]
	v_fmac_f32_e32 v10, v34, v36
	v_mul_f32_e32 v34, v34, v37
	v_fmac_f32_e32 v6, v31, v36
	v_mul_f32_e32 v31, v31, v37
	v_add_u32_e32 v242, 0xa000, v147
	ds_read_b128 v[190:193], v242 offset:32768
	v_fmac_f32_e32 v4, v28, v36
	v_mul_f32_e32 v28, v28, v37
	v_fmac_f32_e32 v11, v18, v36
	v_mul_f32_e32 v18, v18, v37
	v_fmac_f32_e32 v9, v12, v35
	v_mul_f32_e32 v36, v0, v12
	ds_read_b128 v[194:197], v142 offset:40960
	v_fmac_f32_e32 v5, v13, v35
	v_mul_f32_e32 v37, v0, v13
	v_lshl_add_u64 v[12:13], v[94:95], 0, s[60:61]
	v_lshl_or_b32 v175, v138, 2, v135
	global_load_dword v172, v175, s[42:43]
	global_load_dword v173, v175, s[36:37]
	ds_read_b128 v[198:201], v146 offset:40960
	global_load_dword v174, v175, s[40:41]
	global_store_dword v[96:97], v16, off offset:256 nt
	v_mul_f32_e32 v16, v29, v8
	v_fmac_f32_e32 v24, v33, v39
	v_mul_f32_e32 v33, v33, v38
	v_fmac_f32_e32 v21, v30, v39
	v_add_u32_e32 v242, 0xa000, v146
	ds_read_b128 v[202:205], v242 offset:32768
	v_mul_f32_e32 v30, v30, v38
	v_fmac_f32_e32 v19, v27, v39
	v_mul_f32_e32 v27, v27, v38
	v_fmac_f32_e32 v7, v17, v39
	v_mul_f32_e32 v38, v17, v38
	v_fmac_f32_e32 v2, v14, v35
	v_add_u32_e32 v242, 0xa000, v142
	ds_read_b128 v[206:209], v242 offset:32768
	v_mul_f32_e32 v14, v0, v14
	v_fmac_f32_e32 v15, v22, v35
	v_mul_f32_e32 v0, v0, v22
	v_fmac_f32_e32 v23, v29, v1
	v_cvt_pk_bf16_f32 v22, v23, v16
	v_lshl_add_u64 v[16:17], v[12:13], 0, v[88:89]
	global_store_dword v[16:17], v22, off nt
	ds_read_b128 v[210:213], v141 offset:40960
	v_fmac_f32_e32 v20, v26, v1
	v_mul_f32_e32 v16, v26, v8
	v_cvt_pk_bf16_f32 v20, v20, v16
	v_lshl_add_u64 v[16:17], v[12:13], 0, v[98:99]
	global_store_dword v[16:17], v20, off nt
	v_fmac_f32_e32 v3, v40, v1
	v_mul_f32_e32 v16, v40, v8
	v_cvt_pk_bf16_f32 v3, v3, v16
	ds_read_b128 v[214:217], v144 offset:40960
	v_lshl_add_u64 v[16:17], v[12:13], 0, v[100:101]
	global_store_dword v[16:17], v3, off nt
	v_mul_f32_e32 v3, v33, v8
	v_fmac_f32_e32 v24, v33, v1
	v_cvt_pk_bf16_f32 v3, v24, v3
	v_lshl_add_u64 v[16:17], v[12:13], 0, v[102:103]
	global_store_dword v[16:17], v3, off nt
	v_add_u32_e32 v242, 0xa000, v144
	ds_read_b128 v[218:221], v242 offset:32768
	v_mul_f32_e32 v3, v30, v8
	v_fmac_f32_e32 v21, v30, v1
	v_cvt_pk_bf16_f32 v3, v21, v3
	v_lshl_add_u64 v[16:17], v[12:13], 0, v[104:105]
	global_store_dword v[16:17], v3, off nt
	v_mul_f32_e32 v3, v27, v8
	v_fmac_f32_e32 v19, v27, v1
	v_cvt_pk_bf16_f32 v3, v19, v3
	v_add_u32_e32 v242, 0xa000, v141
	ds_read_b128 v[222:225], v242 offset:32768
	v_lshl_add_u64 v[16:17], v[12:13], 0, v[106:107]
	global_store_dword v[16:17], v3, off nt
	v_mul_f32_e32 v3, v38, v8
	v_fmac_f32_e32 v7, v38, v1
	v_cvt_pk_bf16_f32 v3, v7, v3
	v_lshl_add_u64 v[16:17], v[12:13], 0, v[108:109]
	global_store_dword v[16:17], v3, off nt
	ds_read_b128 v[226:229], v139 offset:40960
	v_mul_f32_e32 v3, v34, v8
	v_fmac_f32_e32 v10, v34, v1
	v_cvt_pk_bf16_f32 v3, v10, v3
	v_lshl_add_u64 v[16:17], v[12:13], 0, v[110:111]
	global_store_dword v[16:17], v3, off nt
	v_fmac_f32_e32 v6, v31, v1
	v_mul_f32_e32 v3, v31, v8
	v_cvt_pk_bf16_f32 v3, v6, v3
	ds_read_b128 v[230:233], v143 offset:40960
	v_lshl_add_u64 v[6:7], v[12:13], 0, v[112:113]
	global_store_dword v[6:7], v3, off nt
	v_mul_f32_e32 v3, v28, v8
	v_fmac_f32_e32 v4, v28, v1
	v_cvt_pk_bf16_f32 v3, v4, v3
	v_lshl_add_u64 v[6:7], v[12:13], 0, v[114:115]
	global_store_dword v[6:7], v3, off nt
	v_add_u32_e32 v242, 0xa000, v143
	ds_read_b128 v[234:237], v242 offset:32768
	v_mul_f32_e32 v3, v18, v8
	v_fmac_f32_e32 v11, v18, v1
	v_cvt_pk_bf16_f32 v3, v11, v3
	v_lshl_add_u64 v[6:7], v[12:13], 0, v[116:117]
	global_store_dword v[6:7], v3, off nt
	v_mul_f32_e32 v3, v36, v8
	v_fmac_f32_e32 v9, v36, v1
	v_cvt_pk_bf16_f32 v3, v9, v3
	v_add_u32_e32 v242, 0xa000, v139
	ds_read_b128 v[238:241], v242 offset:32768
	v_lshl_add_u64 v[6:7], v[12:13], 0, v[118:119]
	global_store_dword v[6:7], v3, off nt
	v_fmac_f32_e32 v5, v37, v1
	v_mul_f32_e32 v3, v37, v8
	v_cvt_pk_bf16_f32 v3, v5, v3
	v_lshl_add_u64 v[4:5], v[12:13], 0, v[120:121]
	global_store_dword v[4:5], v3, off nt
	v_fmac_f32_e32 v2, v14, v1
	v_mul_f32_e32 v3, v14, v8
	v_cvt_pk_bf16_f32 v4, v2, v3
	v_lshl_add_u64 v[2:3], v[12:13], 0, v[122:123]
	v_fmac_f32_e32 v15, v0, v1
	v_mul_f32_e32 v0, v0, v8
	global_store_dword v[2:3], v4, off nt
	v_cvt_pk_bf16_f32 v2, v15, v0
	v_lshl_add_u64 v[0:1], v[12:13], 0, v[124:125]
	global_store_dword v[0:1], v2, off nt
	s_and_saveexec_b64 s[12:13], s[6:7]
	s_cbranch_execz .LBB0_288
	v_add_u32_e32 v12, 0x1000, v90
	ds_read2_b64 v[0:3], v12 offset0:192 offset1:224
	ds_read2_b64 v[4:7], v12 offset0:128 offset1:160
	ds_read2_b64 v[8:11], v12 offset0:64 offset1:96
	ds_read2_b64 v[12:15], v12 offset1:32
	s_waitcnt lgkmcnt(3)
	v_fma_f32 v16, 0, v2, v3
	v_pk_mul_f32 v[2:3], v[2:3], v[0:1]
	v_fma_f32 v0, v0, v16, v1
	s_waitcnt lgkmcnt(2)
	v_fma_f32 v0, v6, v0, v7
	v_fma_f32 v0, v4, v0, v5
	s_waitcnt lgkmcnt(1)
	v_fma_f32 v1, v10, v0, v11
	v_mov_b32_e32 v0, v2
	v_mov_b32_e32 v16, v6
	v_mov_b32_e32 v17, v8
	v_pk_mul_f32 v[2:3], v[2:3], v[6:7]
	v_pk_fma_f32 v[0:1], v[0:1], v[16:17], v[8:9]
	v_pk_mul_f32 v[2:3], v[2:3], v[4:5]
	s_waitcnt lgkmcnt(0)
	v_mov_b32_e32 v11, v14
	v_mov_b32_e32 v3, v1
	v_pk_mul_f32 v[0:1], v[2:3], v[10:11]
	v_pk_fma_f32 v[2:3], v[2:3], v[10:11], v[14:15]
	v_pk_mul_f32 v[0:1], v[0:1], v[8:9]
	v_mov_b32_e32 v4, v14
	v_mov_b32_e32 v2, v0
	v_mov_b32_e32 v5, v12
	v_pk_mul_f32 v[0:1], v[0:1], v[14:15]
	v_pk_fma_f32 v[2:3], v[2:3], v[4:5], v[12:13]
	v_pk_mul_f32 v[0:1], v[0:1], v[12:13]
	v_add_u32_e32 v2, 64, v92
	v_mov_b32_e32 v1, v3
	v_ashrrev_i32_e32 v3, 31, v2
	v_lshl_add_u64 v[2:3], v[2:3], 3, s[30:31]
	global_store_dwordx2 v[2:3], v[0:1], off

.LBB0_331:
	v_lshl_add_u64 v[126:127], s[36:37], 0, v[88:89]
	v_lshl_add_u64 v[128:129], s[40:41], 0, v[88:89]
	v_lshl_add_u64 v[130:131], s[42:43], 0, v[88:89]
	v_cndmask_b32_e64 v1, v13, 1.0, s[0:1]
	ds_read_b128 v[178:181], v148 offset:24576
	v_cndmask_b32_e64 v2, v10, 0, s[0:1]
	v_cndmask_b32_e64 v10, v42, v15, s[0:1]
	v_cndmask_b32_e64 v13, v17, v14, s[0:1]
	v_cndmask_b32_e64 v14, v46, v43, s[0:1]
	v_cndmask_b32_e64 v15, v44, v41, s[0:1]
	s_ashr_i32 s9, s8, 31
	v_lshlrev_b32_e32 v88, 2, v94
	v_cndmask_b32_e64 v17, v96, v47, s[0:1]
	ds_read_b128 v[182:185], v148 offset:57344
	v_cndmask_b32_e64 v41, v91, v45, s[0:1]
	v_fmac_f32_e32 v18, v32, v2
	v_mul_f32_e32 v32, v1, v32
	v_fmac_f32_e32 v31, v33, v2
	v_mul_f32_e32 v33, v1, v33
	v_fmac_f32_e32 v30, v34, v2
	v_mul_f32_e32 v34, v1, v34
	v_fmac_f32_e32 v29, v35, v2
	ds_read_b128 v[186:189], v150 offset:24576
	v_mul_f32_e32 v1, v1, v35
	v_fmac_f32_e32 v19, v20, v13
	v_mul_f32_e32 v2, v20, v10
	v_fmac_f32_e32 v28, v36, v13
	v_mul_f32_e32 v20, v36, v10
	v_fmac_f32_e32 v27, v37, v13
	v_mul_f32_e32 v35, v37, v10
	v_fmac_f32_e32 v26, v38, v13
	ds_read_b128 v[190:193], v150 offset:57344
	v_mul_f32_e32 v10, v38, v10
	v_fmac_f32_e32 v23, v12, v15
	v_mul_f32_e32 v38, v12, v14
	v_lshl_add_u64 v[12:13], s[22:23], 0, v[88:89]
	s_lshl_b64 s[4:5], s[8:9], 12
	v_fmac_f32_e32 v24, v40, v15
	v_mul_f32_e32 v37, v40, v14
	v_fmac_f32_e32 v7, v4, v41
	ds_read_b128 v[194:197], v145 offset:24576
	v_mul_f32_e32 v40, v4, v17
	v_lshl_add_u64 v[94:95], v[12:13], 0, s[4:5]
	v_lshlrev_b32_e32 v12, 14, v93
	v_mul_f32_e32 v4, v32, v0
	v_mov_b32_e32 v13, v89
	v_fmac_f32_e32 v18, v32, v3
	v_cvt_pk_bf16_f32 v4, v18, v4
	v_lshl_add_u64 v[96:97], v[94:95], 0, v[12:13]
	global_load_dword v172, v[130:131], off offset:128
	ds_read_b128 v[198:201], v145 offset:57344
	global_load_dword v173, v[126:127], off offset:128
	global_load_dword v174, v[128:129], off offset:128
	global_store_dword v[96:97], v4, off nt
	v_mul_f32_e32 v4, v33, v0
	v_or_b32_e32 v88, 0x1000, v12
	v_fmac_f32_e32 v21, v22, v15
	v_mul_f32_e32 v22, v22, v14
	v_fmac_f32_e32 v25, v39, v15
	ds_read_b128 v[202:205], v149 offset:24576
	v_mul_f32_e32 v36, v39, v14
	v_fmac_f32_e32 v31, v33, v3
	v_cvt_pk_bf16_f32 v4, v31, v4
	v_lshl_add_u64 v[14:15], v[94:95], 0, v[88:89]
	v_or_b32_e32 v98, 0x2000, v12
	v_mov_b32_e32 v99, v89
	global_store_dword v[14:15], v4, off nt
	v_mul_f32_e32 v4, v34, v0
	v_lshl_add_u64 v[14:15], v[94:95], 0, v[98:99]
	ds_read_b128 v[206:209], v149 offset:57344
	v_fmac_f32_e32 v29, v1, v3
	v_mul_f32_e32 v1, v1, v0
	v_or_b32_e32 v100, 0x3000, v12
	v_mov_b32_e32 v101, v89
	v_fmac_f32_e32 v30, v34, v3
	v_cvt_pk_bf16_f32 v4, v30, v4
	global_store_dword v[14:15], v4, off nt
	v_cvt_pk_bf16_f32 v1, v29, v1
	v_lshl_add_u64 v[14:15], v[94:95], 0, v[100:101]
	global_store_dword v[14:15], v1, off nt
	ds_read_b128 v[210:213], v144 offset:24576
	v_mul_f32_e32 v1, v2, v0
	v_or_b32_e32 v102, 0x8000, v12
	v_mov_b32_e32 v103, v89
	v_fmac_f32_e32 v19, v2, v3
	v_cvt_pk_bf16_f32 v1, v19, v1
	v_lshl_add_u64 v[14:15], v[94:95], 0, v[102:103]
	global_store_dword v[14:15], v1, off nt
	v_mul_f32_e32 v1, v20, v0
	v_or_b32_e32 v104, 0x9000, v12
	ds_read_b128 v[214:217], v144 offset:57344
	v_mov_b32_e32 v105, v89
	v_fmac_f32_e32 v28, v20, v3
	v_cvt_pk_bf16_f32 v1, v28, v1
	v_lshl_add_u64 v[14:15], v[94:95], 0, v[104:105]
	global_store_dword v[14:15], v1, off nt
	v_mul_f32_e32 v1, v35, v0
	v_or_b32_e32 v106, 0xa000, v12
	v_mov_b32_e32 v107, v89
	v_fmac_f32_e32 v27, v35, v3
	v_cvt_pk_bf16_f32 v1, v27, v1
	ds_read_b128 v[218:221], v147 offset:24576
	v_lshl_add_u64 v[14:15], v[94:95], 0, v[106:107]
	global_store_dword v[14:15], v1, off nt
	v_mul_f32_e32 v1, v10, v0
	v_or_b32_e32 v108, 0xb000, v12
	v_mov_b32_e32 v109, v89
	v_fmac_f32_e32 v26, v10, v3
	v_cvt_pk_bf16_f32 v1, v26, v1
	v_lshl_add_u64 v[14:15], v[94:95], 0, v[108:109]
	global_store_dword v[14:15], v1, off nt
	ds_read_b128 v[222:225], v147 offset:57344
	v_mul_f32_e32 v1, v22, v0
	v_or_b32_e32 v110, 0x10000, v12
	v_mov_b32_e32 v111, v89
	v_fmac_f32_e32 v21, v22, v3
	v_cvt_pk_bf16_f32 v1, v21, v1
	v_lshl_add_u64 v[14:15], v[94:95], 0, v[110:111]
	global_store_dword v[14:15], v1, off nt
	v_mul_f32_e32 v1, v36, v0
	v_or_b32_e32 v112, 0x11000, v12
	ds_read_b128 v[226:229], v143 offset:24576
	v_mov_b32_e32 v113, v89
	v_fmac_f32_e32 v25, v36, v3
	v_cvt_pk_bf16_f32 v1, v25, v1
	v_lshl_add_u64 v[14:15], v[94:95], 0, v[112:113]
	global_store_dword v[14:15], v1, off nt
	v_mul_f32_e32 v1, v37, v0
	v_or_b32_e32 v114, 0x12000, v12
	v_mov_b32_e32 v115, v89
	v_fmac_f32_e32 v24, v37, v3
	v_cvt_pk_bf16_f32 v1, v24, v1
	ds_read_b128 v[230:233], v143 offset:57344
	v_lshl_add_u64 v[14:15], v[94:95], 0, v[114:115]
	global_store_dword v[14:15], v1, off nt
	v_mul_f32_e32 v1, v38, v0
	v_or_b32_e32 v116, 0x13000, v12
	v_mov_b32_e32 v117, v89
	v_fmac_f32_e32 v8, v16, v41
	v_mul_f32_e32 v16, v16, v17
	v_fmac_f32_e32 v23, v38, v3
	v_cvt_pk_bf16_f32 v1, v23, v1
	ds_read_b128 v[234:237], v146 offset:24576
	v_lshl_add_u64 v[14:15], v[94:95], 0, v[116:117]
	global_store_dword v[14:15], v1, off nt
	v_fmac_f32_e32 v8, v16, v3
	v_mul_f32_e32 v1, v16, v0
	v_or_b32_e32 v118, 0x18000, v12
	v_mov_b32_e32 v119, v89
	v_fmac_f32_e32 v5, v9, v41
	v_mul_f32_e32 v39, v9, v17
	v_cvt_pk_bf16_f32 v1, v8, v1
	ds_read_b128 v[238:241], v146 offset:57344
	v_lshl_add_u64 v[8:9], v[94:95], 0, v[118:119]
	global_store_dword v[8:9], v1, off nt
	v_fmac_f32_e32 v5, v39, v3
	v_mul_f32_e32 v1, v39, v0
	v_or_b32_e32 v120, 0x19000, v12
	v_mov_b32_e32 v121, v89
	v_cvt_pk_bf16_f32 v1, v5, v1
	v_lshl_add_u64 v[4:5], v[94:95], 0, v[120:121]
	v_fmac_f32_e32 v11, v6, v41
	v_mul_f32_e32 v6, v6, v17
	s_lshl_b32 s6, s63, 11
	global_store_dword v[4:5], v1, off nt
	v_mul_f32_e32 v1, v40, v0
	v_or_b32_e32 v122, 0x1a000, v12
	v_mov_b32_e32 v123, v89
	s_or_b32 s6, s6, s70
	v_fmac_f32_e32 v7, v40, v3
	v_cvt_pk_bf16_f32 v1, v7, v1
	v_lshl_add_u64 v[4:5], v[94:95], 0, v[122:123]
	v_mul_f32_e32 v0, v6, v0
	v_or_b32_e32 v124, 0x1b000, v12
	v_mov_b32_e32 v125, v89
	v_lshl_add_u32 v142, v92, 3, 16
	v_cmp_gt_i32_e64 s[4:5], 32, v92
	v_add_u32_e32 v92, s6, v92
	global_store_dword v[4:5], v1, off nt
	v_fmac_f32_e32 v11, v6, v3
	v_cvt_pk_bf16_f32 v2, v11, v0
	v_lshl_add_u64 v[0:1], v[94:95], 0, v[124:125]
	global_store_dword v[0:1], v2, off nt
	s_and_saveexec_b64 s[6:7], s[4:5]
	s_cbranch_execz .LBB0_333
	ds_read2_b64 v[0:3], v142 offset1:32
	ds_read2_b64 v[4:7], v142 offset0:64 offset1:96
	ds_read2_b64 v[8:11], v142 offset0:128 offset1:160
	ds_read2_b64 v[12:15], v142 offset0:192 offset1:224
	v_ashrrev_i32_e32 v93, 31, v92
	s_waitcnt lgkmcnt(3)
	v_fma_f32 v16, 0, v0, v1
	v_pk_mul_f32 v[0:1], v[0:1], v[2:3]
	v_fma_f32 v2, v2, v16, v3
	s_waitcnt lgkmcnt(2)
	v_fma_f32 v2, v4, v2, v5
	v_fma_f32 v2, v6, v2, v7
	s_waitcnt lgkmcnt(1)
	v_fma_f32 v3, v8, v2, v9
	v_mov_b32_e32 v2, v0
	v_mov_b32_e32 v16, v4
	v_mov_b32_e32 v17, v10
	v_pk_mul_f32 v[0:1], v[0:1], v[4:5]
	v_pk_fma_f32 v[2:3], v[2:3], v[16:17], v[10:11]
	v_pk_mul_f32 v[0:1], v[0:1], v[6:7]
	s_waitcnt lgkmcnt(0)
	v_mov_b32_e32 v9, v12
	v_mov_b32_e32 v1, v3
	v_pk_mul_f32 v[2:3], v[0:1], v[8:9]
	v_pk_fma_f32 v[0:1], v[0:1], v[8:9], v[12:13]
	v_pk_mul_f32 v[2:3], v[2:3], v[10:11]
	v_mov_b32_e32 v4, v12
	v_mov_b32_e32 v0, v2
	v_mov_b32_e32 v5, v14
	v_pk_mul_f32 v[2:3], v[2:3], v[12:13]
	v_pk_fma_f32 v[0:1], v[0:1], v[4:5], v[14:15]
	v_pk_mul_f32 v[2:3], v[2:3], v[14:15]
	s_nop 0
	v_mov_b32_e32 v3, v1
	v_lshl_add_u64 v[0:1], v[92:93], 3, s[24:25]
	global_store_dwordx2 v[0:1], v[2:3], off

.LBB0_344:
	v_cndmask_b32_e64 v1, v13, 1.0, s[0:1]
	v_cndmask_b32_e64 v2, v10, 0, s[0:1]
	v_cndmask_b32_e64 v10, v42, v15, s[0:1]
	v_cndmask_b32_e64 v13, v17, v14, s[0:1]
	ds_read_b128 v[178:181], v148 offset:32768
	v_cndmask_b32_e64 v14, v46, v43, s[0:1]
	v_cndmask_b32_e64 v15, v44, v41, s[0:1]
	v_cndmask_b32_e64 v17, v93, v47, s[0:1]
	v_cndmask_b32_e64 v41, v91, v45, s[0:1]
	v_fmac_f32_e32 v18, v32, v2
	v_mul_f32_e32 v32, v1, v32
	ds_read_b128 v[182:185], v150 offset:32768
	v_fmac_f32_e32 v31, v33, v2
	v_mul_f32_e32 v33, v1, v33
	v_fmac_f32_e32 v30, v34, v2
	v_mul_f32_e32 v34, v1, v34
	v_fmac_f32_e32 v29, v35, v2
	v_mul_f32_e32 v1, v1, v35
	v_add_u32_e32 v242, 0x8000, v148
	ds_read_b128 v[186:189], v242 offset:32768
	v_fmac_f32_e32 v27, v37, v13
	v_mul_f32_e32 v35, v37, v10
	v_fmac_f32_e32 v24, v40, v15
	v_mul_f32_e32 v37, v40, v14
	v_fmac_f32_e32 v9, v4, v41
	v_mul_f32_e32 v40, v4, v17
	v_add_u32_e32 v242, 0x8000, v150
	ds_read_b128 v[190:193], v242 offset:32768
	v_mul_f32_e32 v4, v32, v0
	v_fmac_f32_e32 v18, v32, v3
	v_cvt_pk_bf16_f32 v4, v18, v4
	v_fmac_f32_e32 v19, v20, v13
	v_mul_f32_e32 v2, v20, v10
	v_fmac_f32_e32 v28, v36, v13
	v_mul_f32_e32 v20, v36, v10
	ds_read_b128 v[194:197], v145 offset:32768
	v_fmac_f32_e32 v26, v38, v13
	v_mul_f32_e32 v10, v38, v10
	v_fmac_f32_e32 v23, v12, v15
	v_mul_f32_e32 v38, v12, v14
	v_lshl_add_u64 v[12:13], v[94:95], 0, s[38:39]
	global_load_dword v172, v[130:131], off offset:256
	ds_read_b128 v[198:201], v149 offset:32768
	global_load_dword v173, v[126:127], off offset:256
	global_load_dword v174, v[128:129], off offset:256
	global_store_dword v[96:97], v4, off offset:128 nt
	v_mul_f32_e32 v4, v33, v0
	v_fmac_f32_e32 v21, v22, v15
	v_mul_f32_e32 v22, v22, v14
	v_add_u32_e32 v242, 0x8000, v149
	ds_read_b128 v[202:205], v242 offset:32768
	v_fmac_f32_e32 v25, v39, v15
	v_mul_f32_e32 v36, v39, v14
	v_fmac_f32_e32 v31, v33, v3
	v_cvt_pk_bf16_f32 v4, v31, v4
	v_lshl_add_u64 v[14:15], v[12:13], 0, v[88:89]
	global_store_dword v[14:15], v4, off nt
	v_mul_f32_e32 v4, v34, v0
	v_add_u32_e32 v242, 0x8000, v145
	ds_read_b128 v[206:209], v242 offset:32768
	v_lshl_add_u64 v[14:15], v[12:13], 0, v[98:99]
	v_fmac_f32_e32 v29, v1, v3
	v_mul_f32_e32 v1, v1, v0
	v_fmac_f32_e32 v30, v34, v3
	v_cvt_pk_bf16_f32 v4, v30, v4
	global_store_dword v[14:15], v4, off nt
	v_cvt_pk_bf16_f32 v1, v29, v1
	v_lshl_add_u64 v[14:15], v[12:13], 0, v[100:101]
	ds_read_b128 v[210:213], v144 offset:32768
	global_store_dword v[14:15], v1, off nt
	v_mul_f32_e32 v1, v2, v0
	v_fmac_f32_e32 v19, v2, v3
	v_cvt_pk_bf16_f32 v1, v19, v1
	v_lshl_add_u64 v[14:15], v[12:13], 0, v[102:103]
	global_store_dword v[14:15], v1, off nt
	v_mul_f32_e32 v1, v20, v0
	ds_read_b128 v[214:217], v147 offset:32768
	v_fmac_f32_e32 v28, v20, v3
	v_cvt_pk_bf16_f32 v1, v28, v1
	v_lshl_add_u64 v[14:15], v[12:13], 0, v[104:105]
	global_store_dword v[14:15], v1, off nt
	v_mul_f32_e32 v1, v35, v0
	v_fmac_f32_e32 v27, v35, v3
	v_cvt_pk_bf16_f32 v1, v27, v1
	v_lshl_add_u64 v[14:15], v[12:13], 0, v[106:107]
	v_add_u32_e32 v242, 0x8000, v147
	ds_read_b128 v[218:221], v242 offset:32768
	global_store_dword v[14:15], v1, off nt
	v_mul_f32_e32 v1, v10, v0
	v_fmac_f32_e32 v26, v10, v3
	v_cvt_pk_bf16_f32 v1, v26, v1
	v_lshl_add_u64 v[14:15], v[12:13], 0, v[108:109]
	global_store_dword v[14:15], v1, off nt
	v_mul_f32_e32 v1, v22, v0
	v_add_u32_e32 v242, 0x8000, v144
	ds_read_b128 v[222:225], v242 offset:32768
	v_fmac_f32_e32 v21, v22, v3
	v_cvt_pk_bf16_f32 v1, v21, v1
	v_lshl_add_u64 v[14:15], v[12:13], 0, v[110:111]
	global_store_dword v[14:15], v1, off nt
	v_mul_f32_e32 v1, v36, v0
	v_fmac_f32_e32 v25, v36, v3
	v_cvt_pk_bf16_f32 v1, v25, v1
	v_lshl_add_u64 v[14:15], v[12:13], 0, v[112:113]
	ds_read_b128 v[226:229], v143 offset:32768
	global_store_dword v[14:15], v1, off nt
	v_mul_f32_e32 v1, v37, v0
	v_fmac_f32_e32 v24, v37, v3
	v_cvt_pk_bf16_f32 v1, v24, v1
	v_lshl_add_u64 v[14:15], v[12:13], 0, v[114:115]
	global_store_dword v[14:15], v1, off nt
	v_mul_f32_e32 v1, v38, v0
	ds_read_b128 v[230:233], v146 offset:32768
	v_fmac_f32_e32 v6, v16, v41
	v_mul_f32_e32 v16, v16, v17
	v_fmac_f32_e32 v23, v38, v3
	v_cvt_pk_bf16_f32 v1, v23, v1
	v_lshl_add_u64 v[14:15], v[12:13], 0, v[116:117]
	global_store_dword v[14:15], v1, off nt
	v_fmac_f32_e32 v6, v16, v3
	v_add_u32_e32 v242, 0x8000, v146
	ds_read_b128 v[234:237], v242 offset:32768
	v_mul_f32_e32 v1, v16, v0
	v_fmac_f32_e32 v5, v7, v41
	v_mul_f32_e32 v39, v7, v17
	v_cvt_pk_bf16_f32 v1, v6, v1
	v_lshl_add_u64 v[6:7], v[12:13], 0, v[118:119]
	global_store_dword v[6:7], v1, off nt
	v_fmac_f32_e32 v5, v39, v3
	v_add_u32_e32 v242, 0x8000, v143
	ds_read_b128 v[238:241], v242 offset:32768
	v_mul_f32_e32 v1, v39, v0
	v_cvt_pk_bf16_f32 v1, v5, v1
	v_lshl_add_u64 v[4:5], v[12:13], 0, v[120:121]
	v_fmac_f32_e32 v11, v8, v41
	v_mul_f32_e32 v8, v8, v17
	global_store_dword v[4:5], v1, off nt
	v_mul_f32_e32 v1, v40, v0
	v_fmac_f32_e32 v9, v40, v3
	v_cvt_pk_bf16_f32 v1, v9, v1
	v_lshl_add_u64 v[4:5], v[12:13], 0, v[122:123]
	v_mul_f32_e32 v0, v8, v0
	global_store_dword v[4:5], v1, off nt
	v_fmac_f32_e32 v11, v8, v3
	v_cvt_pk_bf16_f32 v2, v11, v0
	v_lshl_add_u64 v[0:1], v[12:13], 0, v[124:125]
	global_store_dword v[0:1], v2, off nt
	s_and_saveexec_b64 s[8:9], s[4:5]
	s_cbranch_execz .LBB0_346
	v_add_u32_e32 v12, 0x800, v142
	ds_read2_b64 v[0:3], v12 offset1:32
	ds_read2_b64 v[4:7], v12 offset0:64 offset1:96
	ds_read2_b64 v[8:11], v12 offset0:128 offset1:160
	ds_read2_b64 v[12:15], v12 offset0:192 offset1:224
	s_waitcnt lgkmcnt(3)
	v_fma_f32 v16, 0, v0, v1
	v_pk_mul_f32 v[0:1], v[0:1], v[2:3]
	v_fma_f32 v2, v2, v16, v3
	s_waitcnt lgkmcnt(2)
	v_fma_f32 v2, v4, v2, v5
	v_fma_f32 v2, v6, v2, v7
	s_waitcnt lgkmcnt(1)
	v_fma_f32 v3, v8, v2, v9
	v_mov_b32_e32 v2, v0
	v_mov_b32_e32 v16, v4
	v_mov_b32_e32 v17, v10
	v_pk_mul_f32 v[0:1], v[0:1], v[4:5]
	v_pk_fma_f32 v[2:3], v[2:3], v[16:17], v[10:11]
	v_pk_mul_f32 v[0:1], v[0:1], v[6:7]
	s_waitcnt lgkmcnt(0)
	v_mov_b32_e32 v9, v12
	v_mov_b32_e32 v1, v3
	v_pk_mul_f32 v[2:3], v[0:1], v[8:9]
	v_pk_fma_f32 v[0:1], v[0:1], v[8:9], v[12:13]
	v_pk_mul_f32 v[2:3], v[2:3], v[10:11]
	v_mov_b32_e32 v4, v12
	v_mov_b32_e32 v0, v2
	v_mov_b32_e32 v5, v14
	v_pk_mul_f32 v[2:3], v[2:3], v[12:13]
	v_pk_fma_f32 v[0:1], v[0:1], v[4:5], v[14:15]
	v_pk_mul_f32 v[2:3], v[2:3], v[14:15]
	v_add_u32_e32 v0, 32, v92
	v_mov_b32_e32 v3, v1
	v_ashrrev_i32_e32 v1, 31, v0
	v_lshl_add_u64 v[0:1], v[0:1], 3, s[24:25]
	global_store_dwordx2 v[0:1], v[2:3], off

.LBB0_357:
	v_cndmask_b32_e64 v1, v13, 1.0, s[0:1]
	v_cndmask_b32_e64 v2, v10, 0, s[0:1]
	v_cndmask_b32_e64 v10, v42, v15, s[0:1]
	v_cndmask_b32_e64 v13, v17, v14, s[0:1]
	ds_read_b128 v[178:181], v148 offset:40960
	v_cndmask_b32_e64 v14, v46, v43, s[0:1]
	v_cndmask_b32_e64 v15, v44, v41, s[0:1]
	v_cndmask_b32_e64 v17, v93, v47, s[0:1]
	v_cndmask_b32_e64 v41, v91, v45, s[0:1]
	v_fmac_f32_e32 v18, v32, v2
	v_mul_f32_e32 v32, v1, v32
	ds_read_b128 v[182:185], v150 offset:40960
	v_fmac_f32_e32 v31, v33, v2
	v_mul_f32_e32 v33, v1, v33
	v_fmac_f32_e32 v30, v34, v2
	v_mul_f32_e32 v34, v1, v34
	v_fmac_f32_e32 v29, v35, v2
	v_mul_f32_e32 v1, v1, v35
	v_add_u32_e32 v242, 0xa000, v148
	ds_read_b128 v[186:189], v242 offset:32768
	v_fmac_f32_e32 v27, v37, v13
	v_mul_f32_e32 v35, v37, v10
	v_fmac_f32_e32 v24, v40, v15
	v_mul_f32_e32 v37, v40, v14
	v_fmac_f32_e32 v9, v4, v41
	v_mul_f32_e32 v40, v4, v17
	v_add_u32_e32 v242, 0xa000, v150
	ds_read_b128 v[190:193], v242 offset:32768
	v_mul_f32_e32 v4, v32, v0
	v_fmac_f32_e32 v18, v32, v3
	v_cvt_pk_bf16_f32 v4, v18, v4
	v_fmac_f32_e32 v19, v20, v13
	v_mul_f32_e32 v2, v20, v10
	v_fmac_f32_e32 v28, v36, v13
	v_mul_f32_e32 v20, v36, v10
	ds_read_b128 v[194:197], v145 offset:40960
	v_fmac_f32_e32 v26, v38, v13
	v_mul_f32_e32 v10, v38, v10
	v_fmac_f32_e32 v23, v12, v15
	v_mul_f32_e32 v38, v12, v14
	v_lshl_add_u64 v[12:13], v[94:95], 0, s[48:49]
	global_load_dword v172, v[130:131], off offset:384
	ds_read_b128 v[198:201], v149 offset:40960
	global_load_dword v173, v[126:127], off offset:384
	global_load_dword v174, v[128:129], off offset:384
	global_store_dword v[96:97], v4, off offset:256 nt
	v_mul_f32_e32 v4, v33, v0
	v_fmac_f32_e32 v21, v22, v15
	v_mul_f32_e32 v22, v22, v14
	v_add_u32_e32 v242, 0xa000, v149
	ds_read_b128 v[202:205], v242 offset:32768
	v_fmac_f32_e32 v25, v39, v15
	v_mul_f32_e32 v36, v39, v14
	v_fmac_f32_e32 v31, v33, v3
	v_cvt_pk_bf16_f32 v4, v31, v4
	v_lshl_add_u64 v[14:15], v[12:13], 0, v[88:89]
	global_store_dword v[14:15], v4, off nt
	v_mul_f32_e32 v4, v34, v0
	v_add_u32_e32 v242, 0xa000, v145
	ds_read_b128 v[206:209], v242 offset:32768
	v_lshl_add_u64 v[14:15], v[12:13], 0, v[98:99]
	v_fmac_f32_e32 v29, v1, v3
	v_mul_f32_e32 v1, v1, v0
	v_fmac_f32_e32 v30, v34, v3
	v_cvt_pk_bf16_f32 v4, v30, v4
	global_store_dword v[14:15], v4, off nt
	v_cvt_pk_bf16_f32 v1, v29, v1
	v_lshl_add_u64 v[14:15], v[12:13], 0, v[100:101]
	ds_read_b128 v[210:213], v144 offset:40960
	global_store_dword v[14:15], v1, off nt
	v_mul_f32_e32 v1, v2, v0
	v_fmac_f32_e32 v19, v2, v3
	v_cvt_pk_bf16_f32 v1, v19, v1
	v_lshl_add_u64 v[14:15], v[12:13], 0, v[102:103]
	global_store_dword v[14:15], v1, off nt
	v_mul_f32_e32 v1, v20, v0
	ds_read_b128 v[214:217], v147 offset:40960
	v_fmac_f32_e32 v28, v20, v3
	v_cvt_pk_bf16_f32 v1, v28, v1
	v_lshl_add_u64 v[14:15], v[12:13], 0, v[104:105]
	global_store_dword v[14:15], v1, off nt
	v_mul_f32_e32 v1, v35, v0
	v_fmac_f32_e32 v27, v35, v3
	v_cvt_pk_bf16_f32 v1, v27, v1
	v_lshl_add_u64 v[14:15], v[12:13], 0, v[106:107]
	v_add_u32_e32 v242, 0xa000, v147
	ds_read_b128 v[218:221], v242 offset:32768
	global_store_dword v[14:15], v1, off nt
	v_mul_f32_e32 v1, v10, v0
	v_fmac_f32_e32 v26, v10, v3
	v_cvt_pk_bf16_f32 v1, v26, v1
	v_lshl_add_u64 v[14:15], v[12:13], 0, v[108:109]
	global_store_dword v[14:15], v1, off nt
	v_mul_f32_e32 v1, v22, v0
	v_add_u32_e32 v242, 0xa000, v144
	ds_read_b128 v[222:225], v242 offset:32768
	v_fmac_f32_e32 v21, v22, v3
	v_cvt_pk_bf16_f32 v1, v21, v1
	v_lshl_add_u64 v[14:15], v[12:13], 0, v[110:111]
	global_store_dword v[14:15], v1, off nt
	v_mul_f32_e32 v1, v36, v0
	v_fmac_f32_e32 v25, v36, v3
	v_cvt_pk_bf16_f32 v1, v25, v1
	v_lshl_add_u64 v[14:15], v[12:13], 0, v[112:113]
	ds_read_b128 v[226:229], v143 offset:40960
	global_store_dword v[14:15], v1, off nt
	v_mul_f32_e32 v1, v37, v0
	v_fmac_f32_e32 v24, v37, v3
	v_cvt_pk_bf16_f32 v1, v24, v1
	v_lshl_add_u64 v[14:15], v[12:13], 0, v[114:115]
	global_store_dword v[14:15], v1, off nt
	v_mul_f32_e32 v1, v38, v0
	ds_read_b128 v[230:233], v146 offset:40960
	v_fmac_f32_e32 v6, v16, v41
	v_mul_f32_e32 v16, v16, v17
	v_fmac_f32_e32 v23, v38, v3
	v_cvt_pk_bf16_f32 v1, v23, v1
	v_lshl_add_u64 v[14:15], v[12:13], 0, v[116:117]
	global_store_dword v[14:15], v1, off nt
	v_fmac_f32_e32 v6, v16, v3
	v_add_u32_e32 v242, 0xa000, v146
	ds_read_b128 v[234:237], v242 offset:32768
	v_mul_f32_e32 v1, v16, v0
	v_fmac_f32_e32 v5, v7, v41
	v_mul_f32_e32 v39, v7, v17
	v_cvt_pk_bf16_f32 v1, v6, v1
	v_lshl_add_u64 v[6:7], v[12:13], 0, v[118:119]
	global_store_dword v[6:7], v1, off nt
	v_fmac_f32_e32 v5, v39, v3
	v_add_u32_e32 v242, 0xa000, v143
	ds_read_b128 v[238:241], v242 offset:32768
	v_mul_f32_e32 v1, v39, v0
	v_cvt_pk_bf16_f32 v1, v5, v1
	v_lshl_add_u64 v[4:5], v[12:13], 0, v[120:121]
	v_fmac_f32_e32 v11, v8, v41
	v_mul_f32_e32 v8, v8, v17
	global_store_dword v[4:5], v1, off nt
	v_mul_f32_e32 v1, v40, v0
	v_fmac_f32_e32 v9, v40, v3
	v_cvt_pk_bf16_f32 v1, v9, v1
	v_lshl_add_u64 v[4:5], v[12:13], 0, v[122:123]
	v_mul_f32_e32 v0, v8, v0
	global_store_dword v[4:5], v1, off nt
	v_fmac_f32_e32 v11, v8, v3
	v_cvt_pk_bf16_f32 v2, v11, v0
	v_lshl_add_u64 v[0:1], v[12:13], 0, v[124:125]
	global_store_dword v[0:1], v2, off nt
	s_and_saveexec_b64 s[8:9], s[4:5]
	s_cbranch_execz .LBB0_359
	v_add_u32_e32 v12, 0x1000, v142
	ds_read2_b64 v[0:3], v12 offset1:32
	ds_read2_b64 v[4:7], v12 offset0:64 offset1:96
	ds_read2_b64 v[8:11], v12 offset0:128 offset1:160
	ds_read2_b64 v[12:15], v12 offset0:192 offset1:224
	s_waitcnt lgkmcnt(3)
	v_fma_f32 v16, 0, v0, v1
	v_pk_mul_f32 v[0:1], v[0:1], v[2:3]
	v_fma_f32 v2, v2, v16, v3
	s_waitcnt lgkmcnt(2)
	v_fma_f32 v2, v4, v2, v5
	v_fma_f32 v2, v6, v2, v7
	s_waitcnt lgkmcnt(1)
	v_fma_f32 v3, v8, v2, v9
	v_mov_b32_e32 v2, v0
	v_mov_b32_e32 v16, v4
	v_mov_b32_e32 v17, v10
	v_pk_mul_f32 v[0:1], v[0:1], v[4:5]
	v_pk_fma_f32 v[2:3], v[2:3], v[16:17], v[10:11]
	v_pk_mul_f32 v[0:1], v[0:1], v[6:7]
	s_waitcnt lgkmcnt(0)
	v_mov_b32_e32 v9, v12
	v_mov_b32_e32 v1, v3
	v_pk_mul_f32 v[2:3], v[0:1], v[8:9]
	v_pk_fma_f32 v[0:1], v[0:1], v[8:9], v[12:13]
	v_pk_mul_f32 v[2:3], v[2:3], v[10:11]
	v_mov_b32_e32 v4, v12
	v_mov_b32_e32 v0, v2
	v_mov_b32_e32 v5, v14
	v_pk_mul_f32 v[2:3], v[2:3], v[12:13]
	v_pk_fma_f32 v[0:1], v[0:1], v[4:5], v[14:15]
	v_pk_mul_f32 v[2:3], v[2:3], v[14:15]
	v_add_u32_e32 v0, 64, v92
	v_mov_b32_e32 v3, v1
	v_ashrrev_i32_e32 v1, 31, v0
	v_lshl_add_u64 v[0:1], v[0:1], 3, s[24:25]
	global_store_dwordx2 v[0:1], v[2:3], off
